# attention loop: next K/V tile pair brought in by LDS-DMA (global_load_lds_dwordx4, lane-linear image = existing layout) instead of VGPR staging + ds_write
# speedup vs baseline: 1.0200x; 1.0200x over previous
; #define AT_LOAD(X, t) do { const size_t adv_ = (size_t)(t) * 64; sk##X = *(const u32x4*)(gk + adv_ * 1024); sv##X = *(const u32x4*)(gv + adv_ * 1024); if (rth) sr##X = *(const u32x4*)(gr + adv_ * 32); } while (0)
; __device__ __forceinline__ void attn_unit(LAS char* lds, const bf16_t* Qp, const bf16_t* KVp, const bf16_t* KRp, int ntiles, bf16_t* Yp, bool dry) {
;     ...
;     const bf16_t* gk = KVp + (size_t)krow * 1024 + kc * 8;
;     const bf16_t* gv = gk + 512;
;     const bf16_t* gr = KRp + (size_t)rrow * 32 + rc * 8;
;     const int lk = krow * AK_PITCH + kc * 16, lr = rrow * AK_PITCH + 128 + rc * 16, lv = (kc >> 2) * 4096 + krow * 64 + (kc & 3) * 16;
;     const bool rth = tid < 256;
;     u32x4 skA, svA, srA = {0u, 0u, 0u, 0u}, skB, svB, srB = {0u, 0u, 0u, 0u};
;     ...
;         if (more) { AT_LOAD(A, t + 2); AT_LOAD(B, t + 3); }
.Latt_iter:
	s_waitcnt vmcnt(0)
	v_xor_b32_e32 v82, 0x80000000, v189
	v_mov_b32_e32 v83, v82
	v_mov_b32_e32 v84, v82
	v_mov_b32_e32 v85, v82
	v_mov_b32_e32 v86, v82
	v_mov_b32_e32 v87, v82
	v_mov_b32_e32 v88, v82
	v_mov_b32_e32 v89, v82
	v_mov_b32_e32 v90, v82
	v_mov_b32_e32 v91, v82
	v_mov_b32_e32 v92, v82
	v_mov_b32_e32 v93, v82
	v_mov_b32_e32 v94, v82
	v_mov_b32_e32 v95, v82
	v_mov_b32_e32 v96, v82
	v_mov_b32_e32 v97, v82
	s_ashr_i32 s14, s8, 6
	s_mul_i32 s2, s14, 0x480000
	s_bfe_u32 s15, s8, 0x30003
	s_lshl_b32 s15, s15, 7
	s_add_i32 s2, s2, s15
	s_add_u32 s2, s2, 0x2f440000
	s_add_u32 s2, s88, s2
	s_addc_u32 s3, s89, 0
	s_mul_i32 s16, s14, 0x24000
	s_add_u32 s16, s16, 0x3cc02000
	s_add_u32 s16, s88, s16
	s_addc_u32 s17, s89, 0
	v_mov_b32_e32 v180, 0x40000
	v_mov_b32_e32 v181, 0x2000
	v_mov_b32_e32 v146, v182
	v_cmp_lt_u32_e32 vcc, 831, v146
	v_cndmask_b32_e64 v147, 0, 1, vcc
	v_mul_u32_u24_e32 v148, 832, v147
	v_sub_u32_e32 v146, v146, v148
	v_mul_u32_u24_e32 v148, 5042, v146
	v_lshrrev_b32_e32 v148, 16, v148
	v_mul_u32_u24_e32 v149, 13, v148
	v_sub_u32_e32 v149, v146, v149
	v_cmp_eq_u32_e32 vcc, 12, v149
	v_cndmask_b32_e64 v149, v149, 0, vcc
	v_lshlrev_b32_e32 v150, 17, v147
	v_lshl_add_u32 v150, v148, 11, v150
	v_lshl_add_u32 v150, v149, 4, v150
	v_lshlrev_b32_e32 v151, 12, v147
	v_lshl_add_u32 v151, v148, 6, v151
	v_lshl_add_u32 v151, v149, 4, v151
	v_add_u32_e32 v151, 0xffffff80, v151
	v_cmp_lt_u32_e64 s[14:15], 7, v149
	v_cndmask_b32_e64 v150, v150, v151, s[14:15]
	v_mov_b32_e32 v152, s2
	v_mov_b32_e32 v153, s3
	v_mov_b32_e32 v178, s16
	v_mov_b32_e32 v179, s17
	v_cndmask_b32_e64 v152, v152, v178, s[14:15]
	v_cndmask_b32_e64 v153, v153, v179, s[14:15]
	v_cndmask_b32_e64 v142, v180, v181, s[14:15]
	v_add_co_u32_e32 v130, vcc, v150, v152
	s_nop 1
	v_addc_co_u32_e32 v131, vcc, 0, v153, vcc
	v_add_u32_e32 v146, 512, v182
	v_cmp_lt_u32_e32 vcc, 831, v146
	v_cndmask_b32_e64 v147, 0, 1, vcc
	v_mul_u32_u24_e32 v148, 832, v147
	v_sub_u32_e32 v146, v146, v148
	v_mul_u32_u24_e32 v148, 5042, v146
	v_lshrrev_b32_e32 v148, 16, v148
	v_mul_u32_u24_e32 v149, 13, v148
	v_sub_u32_e32 v149, v146, v149
	v_cmp_eq_u32_e32 vcc, 12, v149
	v_cndmask_b32_e64 v149, v149, 0, vcc
	v_lshlrev_b32_e32 v150, 17, v147
	v_lshl_add_u32 v150, v148, 11, v150
	v_lshl_add_u32 v150, v149, 4, v150
	v_lshlrev_b32_e32 v151, 12, v147
	v_lshl_add_u32 v151, v148, 6, v151
	v_lshl_add_u32 v151, v149, 4, v151
	v_add_u32_e32 v151, 0xffffff80, v151
	v_cmp_lt_u32_e64 s[14:15], 7, v149
	v_cndmask_b32_e64 v150, v150, v151, s[14:15]
	v_mov_b32_e32 v152, s2
	v_mov_b32_e32 v153, s3
	v_mov_b32_e32 v178, s16
	v_mov_b32_e32 v179, s17
	v_cndmask_b32_e64 v152, v152, v178, s[14:15]
	v_cndmask_b32_e64 v153, v153, v179, s[14:15]
	v_cndmask_b32_e64 v143, v180, v181, s[14:15]
	v_add_co_u32_e32 v132, vcc, v150, v152
	s_nop 1
	v_addc_co_u32_e32 v133, vcc, 0, v153, vcc
	v_add_u32_e32 v146, 1024, v182
	v_cmp_lt_u32_e32 vcc, 831, v146
	v_cndmask_b32_e64 v147, 0, 1, vcc
	v_mul_u32_u24_e32 v148, 832, v147
	v_sub_u32_e32 v146, v146, v148
	v_mul_u32_u24_e32 v148, 5042, v146
	v_lshrrev_b32_e32 v148, 16, v148
	v_mul_u32_u24_e32 v149, 13, v148
	v_sub_u32_e32 v149, v146, v149
	v_cmp_eq_u32_e32 vcc, 12, v149
	v_cndmask_b32_e64 v149, v149, 0, vcc
	v_lshlrev_b32_e32 v150, 17, v147
	v_lshl_add_u32 v150, v148, 11, v150
	v_lshl_add_u32 v150, v149, 4, v150
	v_lshlrev_b32_e32 v151, 12, v147
	v_lshl_add_u32 v151, v148, 6, v151
	v_lshl_add_u32 v151, v149, 4, v151
	v_add_u32_e32 v151, 0xffffff80, v151
	v_cmp_lt_u32_e64 s[14:15], 7, v149
	v_cndmask_b32_e64 v150, v150, v151, s[14:15]
	v_mov_b32_e32 v152, s2
	v_mov_b32_e32 v153, s3
	v_mov_b32_e32 v178, s16
	v_mov_b32_e32 v179, s17
	v_cndmask_b32_e64 v152, v152, v178, s[14:15]
	v_cndmask_b32_e64 v153, v153, v179, s[14:15]
	v_cndmask_b32_e64 v144, v180, v181, s[14:15]
	v_add_co_u32_e32 v134, vcc, v150, v152
	s_nop 1
	v_addc_co_u32_e32 v135, vcc, 0, v153, vcc
	v_add_u32_e32 v146, 1536, v182
	v_cmp_lt_u32_e32 vcc, 831, v146
	v_cndmask_b32_e64 v147, 0, 1, vcc
	v_mul_u32_u24_e32 v148, 832, v147
	v_sub_u32_e32 v146, v146, v148
	v_mul_u32_u24_e32 v148, 5042, v146
	v_lshrrev_b32_e32 v148, 16, v148
	v_mul_u32_u24_e32 v149, 13, v148
	v_sub_u32_e32 v149, v146, v149
	v_cmp_eq_u32_e32 vcc, 12, v149
	v_cndmask_b32_e64 v149, v149, 0, vcc
	v_lshlrev_b32_e32 v150, 17, v147
	v_lshl_add_u32 v150, v148, 11, v150
	v_lshl_add_u32 v150, v149, 4, v150
	v_lshlrev_b32_e32 v151, 12, v147
	v_lshl_add_u32 v151, v148, 6, v151
	v_lshl_add_u32 v151, v149, 4, v151
	v_add_u32_e32 v151, 0xffffff80, v151
	v_cmp_lt_u32_e64 s[14:15], 7, v149
	v_cndmask_b32_e64 v150, v150, v151, s[14:15]
	v_mov_b32_e32 v152, s2
	v_mov_b32_e32 v153, s3
	v_mov_b32_e32 v178, s16
	v_mov_b32_e32 v179, s17
	v_cndmask_b32_e64 v152, v152, v178, s[14:15]
	v_cndmask_b32_e64 v153, v153, v179, s[14:15]
	v_cndmask_b32_e64 v145, v180, v181, s[14:15]
	v_add_co_u32_e32 v136, vcc, v150, v152
	s_nop 1
	v_addc_co_u32_e32 v137, vcc, 0, v153, vcc
	v_bfe_u32 v146, v182, 6, 2
	v_bfe_u32 v147, v182, 2, 4
	v_lshl_add_u32 v146, v146, 4, v147
	v_bfe_u32 v147, v182, 8, 1
	v_and_b32_e32 v148, 3, v182
	v_lshl_add_u32 v147, v147, 2, v148
	v_lshlrev_b32_e32 v146, 11, v146
	v_lshl_add_u32 v146, v147, 4, v146
	v_add_u32_e32 v146, 0x400, v146
	v_mov_b32_e32 v147, s3
	v_add_co_u32_e32 v138, vcc, s2, v146
	s_nop 1
	v_addc_co_u32_e32 v139, vcc, 0, v147, vcc
	v_add_co_u32_e32 v140, vcc, 0x20000, v138
	s_nop 1
	v_addc_co_u32_e32 v141, vcc, 0, v139, vcc
.Latt_loop:
	s_and_b32 s42, s35, 2
	s_mul_i32 s2, s42, 0x3400
	v_add_u32_e32 v0, s2, v209
	v_lshl_add_u32 v185, s42, 13, v208
	v_add_u32_e32 v184, 0x2000, v185
	s_cmp_gt_u32 s35, 33
	s_cbranch_scc1 .Latt_noload
	s_xor_b32 s14, s42, 2
	s_mul_i32 s15, s14, 0x3400
	s_lshl_b32 s16, s29, 10
	s_add_i32 s15, s15, s16
	s_mov_b32 m0, s15
	s_add_i32 s15, s15, 0x2000
	global_load_lds_dwordx4 v[130:131], off
	s_mov_b32 m0, s15
	s_add_i32 s15, s15, 0x2000
	global_load_lds_dwordx4 v[132:133], off
	s_mov_b32 m0, s15
	s_add_i32 s15, s15, 0x2000
	global_load_lds_dwordx4 v[134:135], off
	s_cmp_gt_u32 s29, 1
	s_cbranch_scc1 .Latt_dk3
	s_mov_b32 m0, s15
	s_nop 0
	global_load_lds_dwordx4 v[136:137], off
.Latt_dk3:
	s_lshl_b32 s15, s14, 13
	s_add_i32 s15, s15, s16
	s_add_i32 s15, s15, 0xd000
	s_mov_b32 m0, s15
	s_add_i32 s15, s15, 0x2000
	global_load_lds_dwordx4 v[138:139], off
	s_mov_b32 m0, s15
	s_nop 0
	global_load_lds_dwordx4 v[140:141], off
	v_add_co_u32_e32 v130, vcc, v142, v130
	s_nop 1
	v_addc_co_u32_e32 v131, vcc, 0, v131, vcc
	v_add_co_u32_e32 v132, vcc, v143, v132
	s_nop 1
	v_addc_co_u32_e32 v133, vcc, 0, v133, vcc
	v_add_co_u32_e32 v134, vcc, v144, v134
	s_nop 1
	v_addc_co_u32_e32 v135, vcc, 0, v135, vcc
	v_add_co_u32_e32 v136, vcc, v145, v136
	s_nop 1
	v_addc_co_u32_e32 v137, vcc, 0, v137, vcc
	v_add_co_u32_e32 v138, vcc, 0x40000, v138
	s_nop 1
	v_addc_co_u32_e32 v139, vcc, 0, v139, vcc
	v_add_co_u32_e32 v140, vcc, 0x40000, v140
	s_nop 1
	v_addc_co_u32_e32 v141, vcc, 0, v141, vcc

; #define AT_LOAD(X, t) do { const size_t adv_ = (size_t)(t) * 64; sk##X = *(const u32x4*)(gk + adv_ * 1024); sv##X = *(const u32x4*)(gv + adv_ * 1024); if (rth) sr##X = *(const u32x4*)(gr + adv_ * 32); } while (0)
; #define AT_STORE(X, slot) do { *(LAS u32x4*)(lds + A_K0 + (slot) * AK_BYTES + lk) = sk##X; *(LAS u32x4*)(lds + A_V0 + (slot) * AV_BYTES + lv) = sv##X; if (rth) *(LAS u32x4*)(lds + A_K0 + (slot) * AK_BYTES + lr) = sr##X; } while (0)
; __device__ __forceinline__ void attn_unit(LAS char* lds, const bf16_t* Qp, const bf16_t* KVp, const bf16_t* KRp, int ntiles, bf16_t* Yp, bool dry) {
;     ...
;         if (more) { AT_LOAD(A, t + 2); AT_LOAD(B, t + 3); }
;         AT_SMPV(sb0 + 1, false, pb0, pb1);
;         if (more) { AT_STORE(A, sb0 ^ 2); AT_STORE(B, (sb0 ^ 2) + 1); }
;         __syncthreads();
.Latt_rsback:
.Latt_latch:
	s_cmp_gt_u32 s35, 33
	s_cbranch_scc1 .Latt_nw
	s_waitcnt vmcnt(0)
.Latt_nw:
	s_add_i32 s35, s35, 2
	s_waitcnt lgkmcnt(0)
	s_barrier
	s_cmp_lt_u32 s35, 36
	s_cbranch_scc1 .Latt_loop
	v_and_b32_e32 v3, 64, v203
	v_xor_b32_e32 v2, 32, v203
	v_add_u32_e32 v3, 64, v3
	v_cmp_lt_i32_e32 vcc, v2, v3
	s_nop 1
	v_cndmask_b32_e32 v2, v203, v2, vcc
	v_lshlrev_b32_e32 v98, 2, v2
	s_branch .LBB0_858
